# combined: dilated gather-wait fix + silu(z) loads hoisted to run prologue + work-queue index prefetched in item epilogue
# baseline (speedup 1.0000x reference)
.LBB0_243:
	s_or_b64 exec, exec, s[0:1]
	s_waitcnt lgkmcnt(0)
	v_mov_b32_e32 v0, v254
	s_barrier
	s_mov_b32 s0, 0x46800000
	v_and_b32_e32 v1, 63, v0
	v_lshlrev_b32_e32 v1, 2, v1
	global_load_dword v2, v1, s[24:25]
	global_load_dword v3, v1, s[26:27]
	global_load_dword v4, v1, s[36:37]
	global_load_dword v5, v1, s[38:39]
	global_load_dword v6, v1, s[20:21]
	global_load_dword v7, v1, s[22:23]
	v_mbcnt_lo_u32_b32 v1, -1, 0
	v_mbcnt_hi_u32_b32 v1, -1, v1
	v_and_b32_e32 v8, 64, v1
	v_xor_b32_e32 v9, 1, v1
	v_add_u32_e32 v8, 64, v8
	v_xor_b32_e32 v10, 2, v1
	v_cmp_lt_i32_e32 vcc, v9, v8
	v_xor_b32_e32 v11, 4, v1
	v_xor_b32_e32 v12, 8, v1
	v_cndmask_b32_e32 v9, v1, v9, vcc
	v_cmp_lt_i32_e32 vcc, v10, v8
	v_xor_b32_e32 v13, 16, v1
	v_xor_b32_e32 v14, 32, v1
	v_cndmask_b32_e32 v10, v1, v10, vcc
	v_cmp_lt_i32_e32 vcc, v11, v8
	s_add_u32 s38, s52, 0x3800000
	s_addc_u32 s44, s53, 0
	v_cndmask_b32_e32 v11, v1, v11, vcc
	v_cmp_lt_i32_e32 vcc, v12, v8
	s_add_u32 s45, s52, 0x4800000
	s_addc_u32 s46, s53, 0
	v_cndmask_b32_e32 v12, v1, v12, vcc
	v_cmp_lt_i32_e32 vcc, v13, v8
	s_add_u32 s47, s52, 0x5800000
	s_addc_u32 s48, s53, 0
	v_cndmask_b32_e32 v13, v1, v13, vcc
	v_cmp_lt_i32_e32 vcc, v14, v8
	v_lshlrev_b32_e32 v8, 2, v9
	v_lshlrev_b32_e32 v9, 2, v10
	v_cndmask_b32_e32 v1, v1, v14, vcc
	v_lshlrev_b32_e32 v10, 2, v11
	v_lshlrev_b32_e32 v11, 2, v12
	v_lshlrev_b32_e32 v193, 2, v13
	v_lshlrev_b32_e32 v194, 2, v1
	s_add_u32 s49, s52, 0x6800000
	s_addc_u32 s50, s53, 0
	s_add_u32 s51, s52, 0x7800000
	s_addc_u32 s56, s53, 0
	s_add_u32 s57, s52, 0x8800000
	s_addc_u32 s58, s53, 0
	s_add_u32 s16, s52, 0xb800000
	s_mov_b32 s21, 0
	s_mov_b32 s39, 0x3fb8aa3b
	s_addc_u32 s17, s53, 0
	v_mov_b32_e32 v131, 0
	s_add_i32 s63, 0, 0x20040
	s_movk_i32 s64, 0x70
	v_mov_b32_e32 v195, 0x358637bd
	s_mov_b32 s65, 0x800000
	s_movk_i32 s66, 0xffef
	s_movk_i32 s67, 0xffe7
	v_mov_b32_e32 v196, 0x3f80
	v_mov_b32_e32 v197, 0x3f803f80
	v_mov_b32_e32 v198, 0x42800000
	v_mov_b32_e32 v199, 0xc6ea6000
	s_waitcnt vmcnt(4)
	v_mul_f32_e32 v1, v2, v3
	ds_bpermute_b32 v1, v8, v1
	s_waitcnt vmcnt(2)
	v_mul_f32_e32 v12, v4, v5
	s_waitcnt vmcnt(1)
	v_and_b32_e32 v13, 0x7fffffff, v6
	s_waitcnt vmcnt(0)
	v_and_b32_e32 v14, 0x7fffffff, v7
	ds_bpermute_b32 v12, v8, v12
	ds_bpermute_b32 v13, v8, v13
	ds_bpermute_b32 v8, v8, v14
	v_max_f32_e64 v6, |v6|, |v6|
	s_waitcnt lgkmcnt(3)
	v_fmac_f32_e32 v1, v2, v3
	s_waitcnt lgkmcnt(2)
	v_fmac_f32_e32 v12, v4, v5
	s_waitcnt lgkmcnt(1)
	v_max_f32_e32 v2, v13, v13
	v_max_f32_e64 v7, |v7|, |v7|
	s_waitcnt lgkmcnt(0)
	v_max_f32_e32 v3, v8, v8
	ds_bpermute_b32 v4, v9, v1
	ds_bpermute_b32 v5, v9, v12
	v_max_f32_e32 v2, v6, v2
	v_max_f32_e32 v3, v7, v3
	ds_bpermute_b32 v6, v9, v2
	ds_bpermute_b32 v7, v9, v3
	s_waitcnt lgkmcnt(3)
	v_add_f32_e32 v1, v1, v4
	s_waitcnt lgkmcnt(2)
	v_add_f32_e32 v4, v12, v5
	ds_bpermute_b32 v5, v10, v1
	ds_bpermute_b32 v8, v10, v4
	s_waitcnt lgkmcnt(3)
	v_max_f32_e32 v6, v6, v6
	s_waitcnt lgkmcnt(2)
	v_max_f32_e32 v7, v7, v7
	v_max_f32_e32 v2, v2, v6
	v_max_f32_e32 v3, v3, v7
	ds_bpermute_b32 v6, v10, v2
	ds_bpermute_b32 v7, v10, v3
	s_waitcnt lgkmcnt(3)
	v_add_f32_e32 v1, v1, v5
	s_waitcnt lgkmcnt(2)
	v_add_f32_e32 v4, v4, v8
	ds_bpermute_b32 v5, v11, v1
	ds_bpermute_b32 v8, v11, v4
	s_waitcnt lgkmcnt(3)
	v_max_f32_e32 v6, v6, v6
	s_waitcnt lgkmcnt(2)
	v_max_f32_e32 v7, v7, v7
	v_max_f32_e32 v2, v2, v6
	v_max_f32_e32 v3, v3, v7
	ds_bpermute_b32 v6, v11, v2
	ds_bpermute_b32 v7, v11, v3
	s_waitcnt lgkmcnt(3)
	v_add_f32_e32 v1, v1, v5
	s_waitcnt lgkmcnt(2)
	v_add_f32_e32 v4, v4, v8
	ds_bpermute_b32 v5, v193, v1
	ds_bpermute_b32 v8, v193, v4
	s_waitcnt lgkmcnt(3)
	v_max_f32_e32 v6, v6, v6
	s_waitcnt lgkmcnt(2)
	v_max_f32_e32 v7, v7, v7
	v_max_f32_e32 v2, v2, v6
	v_max_f32_e32 v3, v3, v7
	ds_bpermute_b32 v6, v193, v2
	ds_bpermute_b32 v7, v193, v3
	s_waitcnt lgkmcnt(3)
	v_add_f32_e32 v1, v1, v5
	s_waitcnt lgkmcnt(2)
	v_add_f32_e32 v4, v4, v8
	ds_bpermute_b32 v5, v194, v1
	ds_bpermute_b32 v8, v194, v4
	s_waitcnt lgkmcnt(3)
	v_max_f32_e32 v6, v6, v6
	s_waitcnt lgkmcnt(2)
	v_max_f32_e32 v7, v7, v7
	v_max_f32_e32 v2, v2, v6
	v_max_f32_e32 v3, v3, v7
	s_waitcnt lgkmcnt(1)
	v_add_f32_e32 v1, v1, v5
	s_waitcnt lgkmcnt(0)
	v_add_f32_e32 v4, v4, v8
	ds_bpermute_b32 v5, v194, v2
	ds_bpermute_b32 v6, v194, v3
	v_mul_f32_e32 v1, 0x3fb8aa3b, v1
	v_mul_f32_e32 v4, 0x3fb8aa3b, v4
	v_exp_f32_e32 v1, v1
	v_exp_f32_e32 v4, v4
	s_waitcnt lgkmcnt(1)
	v_max_f32_e32 v5, v5, v5
	s_waitcnt lgkmcnt(0)
	v_max_f32_e32 v6, v6, v6
	v_max_f32_e32 v2, v2, v5
	v_sub_f32_e32 v1, v1, v4
	v_max_f32_e32 v3, v3, v6
	v_add_f32_e32 v180, 0x3e4ccccd, v1
	v_mul_f32_e32 v1, 0x41000000, v2
	v_mul_f32_e32 v1, v1, v3
	v_mul_f32_e32 v1, 0x3f828f5c, v1
	v_mov_b32_e32 v2, 0x41c80000
	v_fmac_f32_e32 v2, 2.0, v1
	v_mul_f32_e32 v1, 4.0, v2
	v_ceil_f32_e32 v1, v1
	v_mov_b32_e32 v3, 0x46800000
	v_cmp_nle_f32_e32 vcc, s0, v1
	v_mov_b32_e32 v181, v180
	s_nop 0
	v_cndmask_b32_e32 v1, v3, v1, vcc
	s_nop 0
	v_readfirstlane_b32 s59, v1
	v_mul_f32_e32 v1, 0x41800000, v2
	v_ceil_f32_e32 v1, v1
	v_cmp_nle_f32_e32 vcc, s0, v1
	s_nop 1
	v_cndmask_b32_e32 v1, v3, v1, vcc
	s_nop 0
	v_readfirstlane_b32 s60, v1
	v_mul_f32_e32 v1, 0x42800000, v2
	v_ceil_f32_e32 v1, v1
	v_cmp_nle_f32_e32 vcc, s0, v1
	s_nop 1
	v_cndmask_b32_e32 v1, v3, v1, vcc
	s_nop 0
	v_readfirstlane_b32 s61, v1
	v_mul_f32_e32 v1, 0x43800000, v2
	v_ceil_f32_e32 v1, v1
	v_cmp_nle_f32_e32 vcc, s0, v1
	v_cmp_eq_u32_e64 s[0:1], 0, v0
	s_nop 0
	v_cndmask_b32_e32 v1, v3, v1, vcc
	s_nop 0
	v_readfirstlane_b32 s62, v1
	s_and_saveexec_b64 s[4:5], s[0:1]
	v_mov_b32_e32 v255, 1
	global_atomic_add v255, v131, v255, s[52:53] sc0
	s_or_b64 exec, exec, s[4:5]
	s_branch .LBB0_246

.LBB0_246:
	s_and_saveexec_b64 s[4:5], s[0:1]
	s_cbranch_execz .LBB0_250
	s_waitcnt vmcnt(0)
	v_mov_b32_e32 v0, v255
	v_mov_b32_e32 v1, s63
	s_nop 0
	ds_write_b32 v1, v0

.LBB0_263:
	v_exp_f32_e32 v80, v80
	v_exp_f32_e32 v81, v81
	v_exp_f32_e32 v82, v82
	v_exp_f32_e32 v83, v83
	v_add_f32_e32 v96, 0, v80
	v_exp_f32_e32 v84, v84
	v_add_f32_e32 v96, v81, v96
	v_exp_f32_e32 v85, v85
	v_add_f32_e32 v96, v82, v96
	v_exp_f32_e32 v86, v86
	v_add_f32_e32 v96, v83, v96
	v_exp_f32_e32 v87, v87
	v_add_f32_e32 v96, v84, v96
	v_exp_f32_e32 v88, v88
	v_add_f32_e32 v96, v85, v96
	v_exp_f32_e32 v89, v89
	v_add_f32_e32 v96, v86, v96
	v_exp_f32_e32 v90, v90
	v_add_f32_e32 v96, v87, v96
	v_exp_f32_e32 v91, v91
	v_add_f32_e32 v96, v88, v96
	v_exp_f32_e32 v92, v92
	v_add_f32_e32 v96, v89, v96
	v_exp_f32_e32 v93, v93
	v_add_f32_e32 v96, v90, v96
	v_exp_f32_e32 v94, v94
	v_add_f32_e32 v96, v91, v96
	v_exp_f32_e32 v95, v95
	v_add_f32_e32 v96, v92, v96
	v_add_f32_e32 v96, v93, v96
	v_add_f32_e32 v96, v94, v96
	v_cvt_pk_bf16_f32 v80, v80, v81
	v_cvt_pk_bf16_f32 v81, v82, v83
	v_cvt_pk_bf16_f32 v82, v84, v85
	v_cvt_pk_bf16_f32 v84, v88, v89
	v_exp_f32_e32 v88, v64
	v_exp_f32_e32 v89, v65
	v_exp_f32_e32 v101, v76
	v_exp_f32_e32 v102, v77
	v_add_f32_e32 v96, v95, v96
	v_cvt_pk_bf16_f32 v83, v86, v87
	v_cvt_pk_bf16_f32 v85, v90, v91
	v_cvt_pk_bf16_f32 v86, v92, v93
	v_cvt_pk_bf16_f32 v87, v94, v95
	v_exp_f32_e32 v90, v66
	v_exp_f32_e32 v91, v67
	v_exp_f32_e32 v92, v68
	v_exp_f32_e32 v93, v69
	v_exp_f32_e32 v94, v70
	v_exp_f32_e32 v95, v71
	v_exp_f32_e32 v97, v72
	v_exp_f32_e32 v98, v73
	v_exp_f32_e32 v99, v74
	v_exp_f32_e32 v100, v75
	v_exp_f32_e32 v103, v78
	v_exp_f32_e32 v104, v79
	s_not_b32 s4, s70
	s_lshl_b32 s4, s4, 15
	s_and_b32 s4, s4, 0x8000
	v_cvt_pk_bf16_f32 v64, v88, v89
	v_cvt_pk_bf16_f32 v70, v101, v102
	v_cvt_pk_bf16_f32 v65, v90, v91
	v_cvt_pk_bf16_f32 v66, v92, v93
	v_cvt_pk_bf16_f32 v67, v94, v95
	v_cvt_pk_bf16_f32 v68, v97, v98
	v_cvt_pk_bf16_f32 v69, v99, v100
	v_cvt_pk_bf16_f32 v71, v103, v104
	s_add_i32 s4, s4, 0
	v_add_u32_e32 v105, s4, v165
	v_add_u32_e32 v107, s4, v167
	v_add_u32_e32 v106, s4, v166
	ds_read_b64_tr_b16 v[72:73], v105 offset:16384
	ds_read_b64_tr_b16 v[74:75], v106 offset:16384
	v_add_u32_e32 v108, s4, v168
	ds_read_b64_tr_b16 v[76:77], v107 offset:16384
	ds_read_b64_tr_b16 v[78:79], v108 offset:16384
	v_add_u32_e32 v109, s4, v161
	v_add_u32_e32 v111, s4, v163
	s_waitcnt lgkmcnt(2)
	v_mfma_f32_32x32x16_bf16 v[48:63], v[72:75], v[80:83], v[48:63]
	v_add_u32_e32 v110, s4, v162
	ds_read_b64_tr_b16 v[72:73], v109 offset:16384
	ds_read_b64_tr_b16 v[74:75], v110 offset:16384
	v_add_u32_e32 v112, s4, v164
	s_waitcnt lgkmcnt(2)
	v_mfma_f32_32x32x16_bf16 v[32:47], v[76:79], v[80:83], v[32:47]
	ds_read_b64_tr_b16 v[76:77], v111 offset:16384
	ds_read_b64_tr_b16 v[78:79], v112 offset:16384
	s_waitcnt lgkmcnt(2)
	v_mfma_f32_32x32x16_bf16 v[16:31], v[72:75], v[80:83], v[16:31]
	s_waitcnt lgkmcnt(0)
	v_mfma_f32_32x32x16_bf16 v[0:15], v[76:79], v[80:83], v[0:15]
	ds_read_b64_tr_b16 v[72:73], v105 offset:20480
	ds_read_b64_tr_b16 v[74:75], v106 offset:20480
	ds_read_b64_tr_b16 v[76:77], v107 offset:20480
	ds_read_b64_tr_b16 v[78:79], v108 offset:20480
	s_waitcnt lgkmcnt(2)
	v_mfma_f32_32x32x16_bf16 v[48:63], v[72:75], v[84:87], v[48:63]
	s_waitcnt lgkmcnt(0)
	v_mfma_f32_32x32x16_bf16 v[32:47], v[76:79], v[84:87], v[32:47]
	ds_read_b64_tr_b16 v[72:73], v109 offset:20480
	ds_read_b64_tr_b16 v[74:75], v110 offset:20480
	ds_read_b64_tr_b16 v[76:77], v111 offset:20480
	ds_read_b64_tr_b16 v[78:79], v112 offset:20480
	s_waitcnt lgkmcnt(2)
	v_mfma_f32_32x32x16_bf16 v[16:31], v[72:75], v[84:87], v[16:31]
	s_waitcnt lgkmcnt(0)
	v_mfma_f32_32x32x16_bf16 v[0:15], v[76:79], v[84:87], v[0:15]
	ds_read_b64_tr_b16 v[72:73], v105 offset:24576
	ds_read_b64_tr_b16 v[74:75], v106 offset:24576
	ds_read_b64_tr_b16 v[76:77], v107 offset:24576
	ds_read_b64_tr_b16 v[78:79], v108 offset:24576
	s_waitcnt lgkmcnt(2)
	v_mfma_f32_32x32x16_bf16 v[48:63], v[72:75], v[64:67], v[48:63]
	s_waitcnt lgkmcnt(0)
	v_mfma_f32_32x32x16_bf16 v[32:47], v[76:79], v[64:67], v[32:47]
	ds_read_b64_tr_b16 v[72:73], v109 offset:24576
	ds_read_b64_tr_b16 v[74:75], v110 offset:24576
	ds_read_b64_tr_b16 v[76:77], v111 offset:24576
	ds_read_b64_tr_b16 v[78:79], v112 offset:24576
	s_waitcnt lgkmcnt(2)
	v_mfma_f32_32x32x16_bf16 v[16:31], v[72:75], v[64:67], v[16:31]
	s_waitcnt lgkmcnt(0)
	v_mfma_f32_32x32x16_bf16 v[0:15], v[76:79], v[64:67], v[0:15]
	ds_read_b64_tr_b16 v[64:65], v105 offset:28672
	ds_read_b64_tr_b16 v[66:67], v106 offset:28672
	ds_read_b64_tr_b16 v[72:73], v107 offset:28672
	ds_read_b64_tr_b16 v[74:75], v108 offset:28672
	s_waitcnt lgkmcnt(2)
	v_mfma_f32_32x32x16_bf16 v[48:63], v[64:67], v[68:71], v[48:63]
	s_waitcnt lgkmcnt(0)
	v_mfma_f32_32x32x16_bf16 v[32:47], v[72:75], v[68:71], v[32:47]
	ds_read_b64_tr_b16 v[64:65], v109 offset:28672
	ds_read_b64_tr_b16 v[66:67], v110 offset:28672
	ds_read_b64_tr_b16 v[72:73], v111 offset:28672
	ds_read_b64_tr_b16 v[74:75], v112 offset:28672
	s_waitcnt lgkmcnt(2)
	v_mfma_f32_32x32x16_bf16 v[16:31], v[64:67], v[68:71], v[16:31]
	s_waitcnt lgkmcnt(0)
	v_mfma_f32_32x32x16_bf16 v[0:15], v[72:75], v[68:71], v[0:15]
	v_add_f32_e32 v64, v88, v96
	v_add_f32_e32 v64, v89, v64
	v_add_f32_e32 v64, v90, v64
	v_add_f32_e32 v64, v91, v64
	v_add_f32_e32 v64, v92, v64
	v_add_f32_e32 v64, v93, v64
	v_add_f32_e32 v64, v94, v64
	v_add_f32_e32 v64, v95, v64
	v_add_f32_e32 v64, v97, v64
	v_add_f32_e32 v64, v98, v64
	v_add_f32_e32 v64, v99, v64
	v_add_f32_e32 v64, v100, v64
	v_add_f32_e32 v64, v101, v64
	v_add_f32_e32 v64, v102, v64
	v_add_f32_e32 v64, v103, v64
	v_add_f32_e32 v64, v104, v64
	v_add_f32_e32 v64, v188, v64
	ds_bpermute_b32 v65, v194, v64
	s_lshl_b32 s6, s69, 14
	s_waitcnt vmcnt(0) lgkmcnt(0)
	s_barrier
	s_and_saveexec_b64 s[98:99], s[0:1]
	s_cbranch_execz .Lqpf_x3
	v_mov_b32_e32 v255, 1
	global_atomic_add v255, v131, v255, s[52:53] sc0

.Lzs_skip:
	global_load_dwordx4 v[80:83], v[0:1], off
	global_load_dwordx4 v[84:87], v[0:1], off offset:32
	global_load_dwordx4 v[88:91], v[2:3], off
	global_load_dwordx4 v[92:95], v[2:3], off offset:32
	global_load_dwordx4 v[96:99], v[0:1], off offset:64
	global_load_dwordx4 v[100:103], v[0:1], off offset:96
	v_min_i32_e32 v0, s79, v7
	v_cmp_gt_i32_e32 vcc, 0, v7
	s_and_b64 s[28:29], s[6:7], exec
	s_cselect_b32 s81, 6, 5
	v_cndmask_b32_e64 v0, v0, 0, vcc
	v_lshlrev_b32_e32 v0, s76, v0
	v_add_u32_e32 v0, s77, v0
	v_ashrrev_i32_e32 v1, 31, v0
	v_lshlrev_b64 v[0:1], 7, v[0:1]
	v_lshl_add_u64 v[4:5], v[128:129], 0, v[0:1]
	v_lshl_add_u64 v[0:1], v[184:185], 0, v[0:1]
	global_load_dwordx4 v[68:71], v[4:5], off
	global_load_dwordx4 v[64:67], v[0:1], off
	v_or_b32_e32 v0, 8, v7
	v_min_i32_e32 v0, s79, v0
	v_cndmask_b32_e64 v0, v0, 0, vcc
	v_lshlrev_b32_e32 v0, s76, v0
	v_add_u32_e32 v0, s77, v0
	v_ashrrev_i32_e32 v1, 31, v0
	v_lshlrev_b64 v[0:1], 7, v[0:1]
	v_lshl_add_u64 v[4:5], v[128:129], 0, v[0:1]
	v_lshl_add_u64 v[0:1], v[184:185], 0, v[0:1]
	global_load_dwordx4 v[76:79], v[4:5], off
	global_load_dwordx4 v[72:75], v[0:1], off
	v_or_b32_e32 v0, 16, v7
	v_min_i32_e32 v0, s79, v0
	v_cndmask_b32_e64 v0, v0, 0, vcc
	v_lshlrev_b32_e32 v0, s76, v0
	v_add_u32_e32 v0, s77, v0
	v_ashrrev_i32_e32 v1, 31, v0
	v_lshlrev_b64 v[0:1], 7, v[0:1]
	v_lshl_add_u64 v[4:5], v[128:129], 0, v[0:1]
	v_lshl_add_u64 v[0:1], v[184:185], 0, v[0:1]
	global_load_dwordx4 v[152:155], v[4:5], off
	global_load_dwordx4 v[148:151], v[0:1], off
	v_or_b32_e32 v0, 24, v7
	v_min_i32_e32 v0, s79, v0
	v_cndmask_b32_e64 v0, v0, 0, vcc
	v_lshlrev_b32_e32 v0, s76, v0
	v_add_u32_e32 v0, s77, v0
	v_ashrrev_i32_e32 v1, 31, v0
	v_lshlrev_b64 v[0:1], 7, v[0:1]
	v_lshl_add_u64 v[4:5], v[128:129], 0, v[0:1]
	v_lshl_add_u64 v[0:1], v[184:185], 0, v[0:1]
	global_load_dwordx4 v[160:163], v[4:5], off
	global_load_dwordx4 v[156:159], v[0:1], off
	global_load_dwordx4 v[104:107], v[2:3], off offset:64
	global_load_dwordx4 v[108:111], v[2:3], off offset:96
	v_mov_b32_e32 v227, 0
	v_mul_f32_e64 v228, v203, -v6
	s_lshl_b32 s82, s81, 5
	v_add_u32_e32 v229, s80, v202
	s_xor_b64 s[36:37], s[6:7], -1
	s_mov_b32 s83, 0
	v_mov_b32_e32 v226, 0
	s_mov_b32 s85, 0
	v_mov_b32_e32 v16, 0
	v_mov_b32_e32 v17, v227
	v_mov_b32_e32 v18, v227
	v_mov_b32_e32 v19, v227
	v_mov_b32_e32 v20, v227
	v_mov_b32_e32 v21, v227
	v_mov_b32_e32 v22, v227
	v_mov_b32_e32 v23, v227
	v_mov_b32_e32 v24, v227
	v_mov_b32_e32 v25, v227
	v_mov_b32_e32 v26, v227
	v_mov_b32_e32 v27, v227
	v_mov_b32_e32 v28, v227
	v_mov_b32_e32 v29, v227
	v_mov_b32_e32 v30, v227
	v_mov_b32_e32 v31, v227
	v_mov_b32_e32 v0, 0
	v_mov_b32_e32 v1, v227
	v_mov_b32_e32 v2, v227
	v_mov_b32_e32 v3, v227
	v_mov_b32_e32 v4, v227
	v_mov_b32_e32 v5, v227
	v_mov_b32_e32 v6, v227
	v_mov_b32_e32 v7, v227
	v_mov_b32_e32 v8, v227
	v_mov_b32_e32 v9, v227
	v_mov_b32_e32 v10, v227
	v_mov_b32_e32 v11, v227
	v_mov_b32_e32 v12, v227
	v_mov_b32_e32 v13, v227
	v_mov_b32_e32 v14, v227
	v_mov_b32_e32 v15, v227
	v_mov_b32_e32 v48, 0
	v_mov_b32_e32 v49, v227
	v_mov_b32_e32 v50, v227
	v_mov_b32_e32 v51, v227
	v_mov_b32_e32 v52, v227
	v_mov_b32_e32 v53, v227
	v_mov_b32_e32 v54, v227
	v_mov_b32_e32 v55, v227
	s_waitcnt vmcnt(9)
	v_mov_b64_e32 v[118:119], v[70:71]
	s_waitcnt vmcnt(8)
	v_mov_b64_e32 v[114:115], v[66:67]
	v_mov_b32_e32 v56, v227
	v_mov_b32_e32 v57, v227
	v_mov_b32_e32 v58, v227
	v_mov_b32_e32 v59, v227
	v_mov_b32_e32 v60, v227
	v_mov_b32_e32 v61, v227
	v_mov_b32_e32 v62, v227
	v_mov_b32_e32 v63, v227
	s_waitcnt vmcnt(7)
	v_mov_b64_e32 v[126:127], v[78:79]
	s_waitcnt vmcnt(6)
	v_mov_b64_e32 v[122:123], v[74:75]
	v_mov_b32_e32 v32, v227
	v_mov_b32_e32 v33, v227
	v_mov_b32_e32 v34, v227
	v_mov_b32_e32 v35, v227
	v_mov_b32_e32 v36, v227
	v_mov_b32_e32 v37, v227
	v_mov_b32_e32 v38, v227
	v_mov_b32_e32 v39, v227
	s_waitcnt vmcnt(5)
	v_mov_b64_e32 v[136:137], v[152:153]
	s_waitcnt vmcnt(4)
	v_mov_b64_e32 v[132:133], v[148:149]
	v_mov_b32_e32 v40, v227
	v_mov_b32_e32 v41, v227
	v_mov_b32_e32 v42, v227
	v_mov_b32_e32 v43, v227
	v_mov_b32_e32 v44, v227
	v_mov_b32_e32 v45, v227
	s_waitcnt vmcnt(3)
	v_mov_b64_e32 v[144:145], v[160:161]
	s_waitcnt vmcnt(0)
	v_mov_b64_e32 v[140:141], v[156:157]
	v_mov_b32_e32 v46, v227
	v_mov_b32_e32 v47, v227
	v_mov_b64_e32 v[112:113], v[64:65]
	v_mov_b64_e32 v[120:121], v[72:73]
	v_mov_b64_e32 v[134:135], v[150:151]
	v_mov_b64_e32 v[142:143], v[158:159]
	v_mov_b64_e32 v[116:117], v[68:69]
	v_mov_b64_e32 v[124:125], v[76:77]
	v_mov_b64_e32 v[138:139], v[154:155]
	v_mov_b64_e32 v[146:147], v[162:163]
	s_add_i32 s84, s85, 1
	s_cmp_ge_u32 s84, s81
	s_cbranch_scc1 .LBB0_273

.LBB0_275:
	s_cmp_eq_u32 s83, 0
	s_cselect_b64 s[28:29], -1, 0
	s_or_b64 s[28:29], s[36:37], s[28:29]
	s_and_b64 vcc, exec, s[28:29]
	s_cbranch_vccnz .LBB0_277
	s_waitcnt lgkmcnt(11)
	v_mfma_f32_32x32x16_bf16 v[64:79], v[176:179], v[88:91], 0
	s_waitcnt lgkmcnt(10)
	v_mfma_f32_32x32x16_bf16 v[64:79], v[172:175], v[92:95], v[64:79]
	v_add_u32_e32 v172, 0xffffffa0, v231
	s_waitcnt lgkmcnt(9)
	v_mfma_f32_32x32x16_bf16 v[64:79], v[168:171], v[104:107], v[64:79]
	v_cvt_f32_i32_e32 v168, v172
	v_add_f32_e32 v169, 1.0, v168
	v_cmp_le_f32_e64 vcc, |v168|, v230
	v_add_f32_e32 v170, 2.0, v168
	s_waitcnt lgkmcnt(8)
	v_mfma_f32_32x32x16_bf16 v[64:79], v[164:167], v[108:111], v[64:79]
	v_add_f32_e32 v171, 0x40400000, v168
	v_add_f32_e32 v172, 4.0, v168
	v_add_f32_e32 v173, 0x40a00000, v168
	v_add_f32_e32 v174, 0x40c00000, v168
	v_add_f32_e32 v165, 0x40e00000, v168
	s_nop 6
	v_fma_f32 v64, v228, |v168|, v64
	v_fma_f32 v65, v228, |v169|, v65
	v_cndmask_b32_e32 v64, v199, v64, vcc
	v_cmp_le_f32_e64 vcc, |v169|, v230
	v_fma_f32 v66, v228, |v170|, v66
	v_fma_f32 v67, v228, |v171|, v67
	v_cndmask_b32_e32 v65, v199, v65, vcc
	v_cmp_le_f32_e64 vcc, |v170|, v230
	v_fma_f32 v68, v228, |v172|, v68
	v_fma_f32 v69, v228, |v173|, v69
	v_cndmask_b32_e32 v66, v199, v66, vcc
	v_cmp_le_f32_e64 vcc, |v171|, v230
	v_exp_f32_e32 v64, v64
	v_fma_f32 v70, v228, |v174|, v70
	v_cndmask_b32_e32 v67, v199, v67, vcc
	v_cmp_le_f32_e64 vcc, |v172|, v230
	v_exp_f32_e32 v65, v65
	v_exp_f32_e32 v66, v66
	v_cndmask_b32_e32 v68, v199, v68, vcc
	v_cmp_le_f32_e64 vcc, |v173|, v230
	v_fma_f32 v71, v228, |v165|, v71
	v_exp_f32_e32 v67, v67
	v_cndmask_b32_e32 v69, v199, v69, vcc
	v_cmp_le_f32_e64 vcc, |v174|, v230
	v_exp_f32_e32 v68, v68
	v_exp_f32_e32 v69, v69
	v_cndmask_b32_e32 v70, v199, v70, vcc
	v_cmp_le_f32_e64 vcc, |v165|, v230
	v_add_f32_e32 v165, 0x41800000, v168
	v_fma_f32 v72, v228, |v165|, v72
	v_cndmask_b32_e32 v71, v199, v71, vcc
	v_cmp_le_f32_e64 vcc, |v165|, v230
	v_add_f32_e32 v165, 0x41880000, v168
	v_add_f32_e32 v164, 0, v64
	v_cndmask_b32_e32 v72, v199, v72, vcc
	v_fma_f32 v73, v228, |v165|, v73
	v_cmp_le_f32_e64 vcc, |v165|, v230
	v_add_f32_e32 v165, 0x41900000, v168
	v_add_f32_e32 v164, v65, v164
	v_exp_f32_e32 v70, v70
	v_exp_f32_e32 v71, v71
	v_cndmask_b32_e32 v73, v199, v73, vcc
	v_fma_f32 v74, v228, |v165|, v74
	v_cmp_le_f32_e64 vcc, |v165|, v230
	v_add_f32_e32 v165, 0x41980000, v168
	v_add_f32_e32 v164, v66, v164
	v_cndmask_b32_e32 v74, v199, v74, vcc
	v_fma_f32 v75, v228, |v165|, v75
	v_cmp_le_f32_e64 vcc, |v165|, v230
	v_add_f32_e32 v165, 0x41a00000, v168
	v_add_f32_e32 v164, v67, v164
	v_cndmask_b32_e32 v75, v199, v75, vcc
	v_fma_f32 v76, v228, |v165|, v76
	v_cmp_le_f32_e64 vcc, |v165|, v230
	v_add_f32_e32 v165, 0x41a80000, v168
	v_add_f32_e32 v164, v68, v164
	v_cndmask_b32_e32 v76, v199, v76, vcc
	v_fma_f32 v77, v228, |v165|, v77
	v_cmp_le_f32_e64 vcc, |v165|, v230
	v_cvt_pk_bf16_f32 v64, v64, v65
	v_cvt_pk_bf16_f32 v65, v66, v67
	v_cvt_pk_bf16_f32 v66, v68, v69
	v_add_f32_e32 v68, 0x41b00000, v168
	v_add_f32_e32 v164, v69, v164
	v_cndmask_b32_e32 v77, v199, v77, vcc
	v_cvt_pk_bf16_f32 v67, v70, v71
	v_fma_f32 v69, v228, |v68|, v78
	v_cmp_le_f32_e64 vcc, |v68|, v230
	s_waitcnt lgkmcnt(6)
	v_mfma_f32_32x32x16_bf16 v[16:31], v[156:159], v[64:67], v[16:31]
	v_add_f32_e32 v164, v70, v164
	v_cndmask_b32_e32 v68, v199, v69, vcc
	v_add_f32_e32 v69, 0x41b80000, v168
	v_fma_f32 v70, v228, |v69|, v79
	v_cmp_le_f32_e64 vcc, |v69|, v230
	v_exp_f32_e32 v72, v72
	v_exp_f32_e32 v73, v73
	s_waitcnt lgkmcnt(2)
	v_mfma_f32_32x32x16_bf16 v[0:15], v[160:163], v[64:67], v[0:15]
	v_cndmask_b32_e32 v64, v199, v70, vcc
	v_exp_f32_e32 v74, v74
	v_exp_f32_e32 v75, v75
	v_exp_f32_e32 v76, v76
	v_exp_f32_e32 v77, v77
	v_exp_f32_e32 v68, v68
	v_exp_f32_e32 v69, v64
	v_add_f32_e32 v164, v71, v164
	v_add_f32_e32 v164, v72, v164
	v_cvt_pk_bf16_f32 v64, v72, v73
	v_cvt_pk_bf16_f32 v65, v74, v75
	v_cvt_pk_bf16_f32 v66, v76, v77
	v_cvt_pk_bf16_f32 v67, v68, v69
	v_add_f32_e32 v70, v73, v164
	v_add_f32_e32 v70, v74, v70
	v_mfma_f32_32x32x16_bf16 v[16:31], v[148:151], v[64:67], v[16:31]
	v_add_f32_e32 v70, v75, v70
	v_add_f32_e32 v70, v76, v70
	v_add_f32_e32 v70, v77, v70
	v_add_f32_e32 v68, v68, v70
	v_add_f32_e32 v68, v69, v68
	v_add_f32_e32 v226, v226, v68
	s_waitcnt lgkmcnt(0)
	v_mfma_f32_32x32x16_bf16 v[0:15], v[152:155], v[64:67], v[0:15]

.LBB0_279:
	s_cmp_lg_u32 s75, 3
	s_cbranch_scc1 .Lqpf_skip2
	s_and_saveexec_b64 s[98:99], s[0:1]
	s_cbranch_execz .Lqpf_x2
	v_mov_b32_e32 v255, 1
	global_atomic_add v255, v131, v255, s[52:53] sc0

.LBB0_307:
	v_exp_f32_e32 v80, v80
	v_exp_f32_e32 v81, v81
	v_exp_f32_e32 v82, v82
	v_exp_f32_e32 v83, v83
	v_add_f32_e32 v96, 0, v80
	v_exp_f32_e32 v84, v84
	v_add_f32_e32 v96, v81, v96
	v_exp_f32_e32 v85, v85
	v_add_f32_e32 v96, v82, v96
	v_exp_f32_e32 v86, v86
	v_add_f32_e32 v96, v83, v96
	v_exp_f32_e32 v87, v87
	v_add_f32_e32 v96, v84, v96
	v_exp_f32_e32 v88, v88
	v_add_f32_e32 v96, v85, v96
	v_exp_f32_e32 v89, v89
	v_add_f32_e32 v96, v86, v96
	v_exp_f32_e32 v90, v90
	v_add_f32_e32 v96, v87, v96
	v_exp_f32_e32 v91, v91
	v_add_f32_e32 v96, v88, v96
	v_exp_f32_e32 v92, v92
	v_add_f32_e32 v96, v89, v96
	v_exp_f32_e32 v93, v93
	v_add_f32_e32 v96, v90, v96
	v_exp_f32_e32 v94, v94
	v_add_f32_e32 v96, v91, v96
	v_exp_f32_e32 v95, v95
	v_add_f32_e32 v96, v92, v96
	v_add_f32_e32 v96, v93, v96
	v_add_f32_e32 v96, v94, v96
	v_cvt_pk_bf16_f32 v80, v80, v81
	v_cvt_pk_bf16_f32 v81, v82, v83
	v_cvt_pk_bf16_f32 v82, v84, v85
	v_cvt_pk_bf16_f32 v84, v88, v89
	v_exp_f32_e32 v88, v64
	v_exp_f32_e32 v89, v65
	v_exp_f32_e32 v101, v76
	v_exp_f32_e32 v102, v77
	v_add_f32_e32 v96, v95, v96
	v_cvt_pk_bf16_f32 v83, v86, v87
	v_cvt_pk_bf16_f32 v85, v90, v91
	v_cvt_pk_bf16_f32 v86, v92, v93
	v_cvt_pk_bf16_f32 v87, v94, v95
	v_exp_f32_e32 v90, v66
	v_exp_f32_e32 v91, v67
	v_exp_f32_e32 v92, v68
	v_exp_f32_e32 v93, v69
	v_exp_f32_e32 v94, v70
	v_exp_f32_e32 v95, v71
	v_exp_f32_e32 v97, v72
	v_exp_f32_e32 v98, v73
	v_exp_f32_e32 v99, v74
	v_exp_f32_e32 v100, v75
	v_exp_f32_e32 v103, v78
	v_exp_f32_e32 v104, v79
	s_not_b32 s4, s20
	s_lshl_b32 s4, s4, 15
	s_and_b32 s4, s4, 0x8000
	v_cvt_pk_bf16_f32 v64, v88, v89
	v_cvt_pk_bf16_f32 v70, v101, v102
	v_cvt_pk_bf16_f32 v65, v90, v91
	v_cvt_pk_bf16_f32 v66, v92, v93
	v_cvt_pk_bf16_f32 v67, v94, v95
	v_cvt_pk_bf16_f32 v68, v97, v98
	v_cvt_pk_bf16_f32 v69, v99, v100
	v_cvt_pk_bf16_f32 v71, v103, v104
	s_add_i32 s4, s4, 0
	v_add_u32_e32 v105, s4, v165
	v_add_u32_e32 v107, s4, v167
	v_add_u32_e32 v106, s4, v166
	ds_read_b64_tr_b16 v[72:73], v105 offset:16384
	ds_read_b64_tr_b16 v[74:75], v106 offset:16384
	v_add_u32_e32 v108, s4, v168
	ds_read_b64_tr_b16 v[76:77], v107 offset:16384
	ds_read_b64_tr_b16 v[78:79], v108 offset:16384
	v_add_u32_e32 v109, s4, v161
	v_add_u32_e32 v111, s4, v163
	s_waitcnt lgkmcnt(2)
	v_mfma_f32_32x32x16_bf16 v[48:63], v[72:75], v[80:83], v[48:63]
	v_add_u32_e32 v110, s4, v162
	ds_read_b64_tr_b16 v[72:73], v109 offset:16384
	ds_read_b64_tr_b16 v[74:75], v110 offset:16384
	v_add_u32_e32 v112, s4, v164
	s_waitcnt lgkmcnt(2)
	v_mfma_f32_32x32x16_bf16 v[32:47], v[76:79], v[80:83], v[32:47]
	ds_read_b64_tr_b16 v[76:77], v111 offset:16384
	ds_read_b64_tr_b16 v[78:79], v112 offset:16384
	s_waitcnt lgkmcnt(2)
	v_mfma_f32_32x32x16_bf16 v[16:31], v[72:75], v[80:83], v[16:31]
	s_waitcnt lgkmcnt(0)
	v_mfma_f32_32x32x16_bf16 v[0:15], v[76:79], v[80:83], v[0:15]
	ds_read_b64_tr_b16 v[72:73], v105 offset:20480
	ds_read_b64_tr_b16 v[74:75], v106 offset:20480
	ds_read_b64_tr_b16 v[76:77], v107 offset:20480
	ds_read_b64_tr_b16 v[78:79], v108 offset:20480
	s_waitcnt lgkmcnt(2)
	v_mfma_f32_32x32x16_bf16 v[48:63], v[72:75], v[84:87], v[48:63]
	s_waitcnt lgkmcnt(0)
	v_mfma_f32_32x32x16_bf16 v[32:47], v[76:79], v[84:87], v[32:47]
	ds_read_b64_tr_b16 v[72:73], v109 offset:20480
	ds_read_b64_tr_b16 v[74:75], v110 offset:20480
	ds_read_b64_tr_b16 v[76:77], v111 offset:20480
	ds_read_b64_tr_b16 v[78:79], v112 offset:20480
	s_waitcnt lgkmcnt(2)
	v_mfma_f32_32x32x16_bf16 v[16:31], v[72:75], v[84:87], v[16:31]
	s_waitcnt lgkmcnt(0)
	v_mfma_f32_32x32x16_bf16 v[0:15], v[76:79], v[84:87], v[0:15]
	ds_read_b64_tr_b16 v[72:73], v105 offset:24576
	ds_read_b64_tr_b16 v[74:75], v106 offset:24576
	ds_read_b64_tr_b16 v[76:77], v107 offset:24576
	ds_read_b64_tr_b16 v[78:79], v108 offset:24576
	s_waitcnt lgkmcnt(2)
	v_mfma_f32_32x32x16_bf16 v[48:63], v[72:75], v[64:67], v[48:63]
	s_waitcnt lgkmcnt(0)
	v_mfma_f32_32x32x16_bf16 v[32:47], v[76:79], v[64:67], v[32:47]
	ds_read_b64_tr_b16 v[72:73], v109 offset:24576
	ds_read_b64_tr_b16 v[74:75], v110 offset:24576
	ds_read_b64_tr_b16 v[76:77], v111 offset:24576
	ds_read_b64_tr_b16 v[78:79], v112 offset:24576
	s_waitcnt lgkmcnt(2)
	v_mfma_f32_32x32x16_bf16 v[16:31], v[72:75], v[64:67], v[16:31]
	s_waitcnt lgkmcnt(0)
	v_mfma_f32_32x32x16_bf16 v[0:15], v[76:79], v[64:67], v[0:15]
	ds_read_b64_tr_b16 v[64:65], v105 offset:28672
	ds_read_b64_tr_b16 v[66:67], v106 offset:28672
	ds_read_b64_tr_b16 v[72:73], v107 offset:28672
	ds_read_b64_tr_b16 v[74:75], v108 offset:28672
	s_waitcnt lgkmcnt(2)
	v_mfma_f32_32x32x16_bf16 v[48:63], v[64:67], v[68:71], v[48:63]
	s_waitcnt lgkmcnt(0)
	v_mfma_f32_32x32x16_bf16 v[32:47], v[72:75], v[68:71], v[32:47]
	ds_read_b64_tr_b16 v[64:65], v109 offset:28672
	ds_read_b64_tr_b16 v[66:67], v110 offset:28672
	ds_read_b64_tr_b16 v[72:73], v111 offset:28672
	ds_read_b64_tr_b16 v[74:75], v112 offset:28672
	s_waitcnt lgkmcnt(2)
	v_mfma_f32_32x32x16_bf16 v[16:31], v[64:67], v[68:71], v[16:31]
	s_waitcnt lgkmcnt(0)
	v_mfma_f32_32x32x16_bf16 v[0:15], v[72:75], v[68:71], v[0:15]
	v_add_f32_e32 v64, v88, v96
	v_add_f32_e32 v64, v89, v64
	v_add_f32_e32 v64, v90, v64
	v_add_f32_e32 v64, v91, v64
	v_add_f32_e32 v64, v92, v64
	v_add_f32_e32 v64, v93, v64
	v_add_f32_e32 v64, v94, v64
	v_add_f32_e32 v64, v95, v64
	v_add_f32_e32 v64, v97, v64
	v_add_f32_e32 v64, v98, v64
	v_add_f32_e32 v64, v99, v64
	v_add_f32_e32 v64, v100, v64
	v_add_f32_e32 v64, v101, v64
	v_add_f32_e32 v64, v102, v64
	v_add_f32_e32 v64, v103, v64
	v_add_f32_e32 v64, v104, v64
	v_add_f32_e32 v64, v188, v64
	ds_bpermute_b32 v65, v194, v64
	s_lshl_b32 s6, s69, 14
	s_waitcnt vmcnt(0) lgkmcnt(0)
	s_barrier
	s_and_saveexec_b64 s[98:99], s[0:1]
	s_cbranch_execz .Lqpf_x1
	v_mov_b32_e32 v255, 1
	global_atomic_add v255, v131, v255, s[52:53] sc0
